# P1 epilogue: 16 sum-of-squares swizzle ladders batched 8 at a time through free registers
# speedup vs baseline: 1.0033x; 1.0033x over previous
;     __device__ __forceinline__ void operator()(PG8_ACC, const Unit& u, int wr, int wc, int fr, int fq) const {
;     ...
;                         const f32x4 a = acc[ai][bj][m][0], b = acc[ai][bj][m][1];
;                         float s = (a[0] * a[0] + a[1] * a[1]) + (a[2] * a[2] + a[3] * a[3]) + (b[0] * b[0] + b[1] * b[1]) + (b[2] * b[2] + b[3] * b[3]);
;                         s += shx<16>(s); s = sum_halves(s);
;                         if (fq == 0) X[((ai * 128 + wr * 64 + m * 16 + fr) * 2 + bj) * 4 + wc] = s;
;                     }
.LBB0_143:
	s_and_b64 vcc, exec, s[52:53]
	v_mov_b32_e32 v152, 1.0
	v_mov_b32_e32 v167, 1.0
	v_mov_b32_e32 v166, 1.0
	v_mov_b32_e32 v163, 1.0
	v_mov_b32_e32 v162, 1.0
	v_mov_b32_e32 v159, 1.0
	v_mov_b32_e32 v158, 1.0
	v_mov_b32_e32 v165, 1.0
	v_mov_b32_e32 v164, 1.0
	v_mov_b32_e32 v161, 1.0
	v_mov_b32_e32 v160, 1.0
	v_mov_b32_e32 v157, 1.0
	v_mov_b32_e32 v156, 1.0
	v_mov_b32_e32 v155, 1.0
	v_mov_b32_e32 v154, 1.0
	v_mov_b32_e32 v131, 1.0
	v_mov_b32_e32 v130, 1.0
	v_mov_b32_e32 v129, 1.0
	v_mov_b32_e32 v128, 1.0
	v_mov_b32_e32 v135, 1.0
	v_mov_b32_e32 v134, 1.0
	v_mov_b32_e32 v133, 1.0
	v_mov_b32_e32 v132, 1.0
	s_cbranch_vccnz .LBB0_177
	v_mul_f32_e32 v198, v125, v125
	v_mul_f32_e32 v214, v127, v127
	v_fmac_f32_e32 v198, v124, v124
	v_fmac_f32_e32 v214, v126, v126
	v_add_f32_e32 v198, v198, v214
	v_mul_f32_e32 v214, v121, v121
	v_fmac_f32_e32 v214, v120, v120
	v_add_f32_e32 v198, v198, v214
	v_mul_f32_e32 v214, v123, v123
	v_fmac_f32_e32 v214, v122, v122
	v_add_f32_e32 v198, v214, v198
	v_mul_f32_e32 v199, v117, v117
	v_mul_f32_e32 v214, v119, v119
	v_fmac_f32_e32 v199, v116, v116
	v_fmac_f32_e32 v214, v118, v118
	v_add_f32_e32 v199, v199, v214
	v_mul_f32_e32 v214, v109, v109
	v_fmac_f32_e32 v214, v108, v108
	v_add_f32_e32 v199, v199, v214
	v_mul_f32_e32 v214, v111, v111
	v_fmac_f32_e32 v214, v110, v110
	v_add_f32_e32 v199, v214, v199
	v_mul_f32_e32 v200, v113, v113
	v_mul_f32_e32 v214, v115, v115
	v_fmac_f32_e32 v200, v112, v112
	v_fmac_f32_e32 v214, v114, v114
	v_add_f32_e32 v200, v200, v214
	v_mul_f32_e32 v214, v105, v105
	v_fmac_f32_e32 v214, v104, v104
	v_add_f32_e32 v200, v200, v214
	v_mul_f32_e32 v214, v107, v107
	v_fmac_f32_e32 v214, v106, v106
	v_add_f32_e32 v200, v214, v200
	v_mul_f32_e32 v201, v101, v101
	v_mul_f32_e32 v214, v103, v103
	v_fmac_f32_e32 v201, v100, v100
	v_fmac_f32_e32 v214, v102, v102
	v_add_f32_e32 v201, v201, v214
	v_mul_f32_e32 v214, v93, v93
	v_fmac_f32_e32 v214, v92, v92
	v_add_f32_e32 v201, v201, v214
	v_mul_f32_e32 v214, v95, v95
	v_fmac_f32_e32 v214, v94, v94
	v_add_f32_e32 v201, v214, v201
	v_mul_f32_e32 v202, v97, v97
	v_mul_f32_e32 v214, v99, v99
	v_fmac_f32_e32 v202, v96, v96
	v_fmac_f32_e32 v214, v98, v98
	v_add_f32_e32 v202, v202, v214
	v_mul_f32_e32 v214, v89, v89
	v_fmac_f32_e32 v214, v88, v88
	v_add_f32_e32 v202, v202, v214
	v_mul_f32_e32 v214, v91, v91
	v_fmac_f32_e32 v214, v90, v90
	v_add_f32_e32 v202, v214, v202
	v_mul_f32_e32 v203, v85, v85
	v_mul_f32_e32 v214, v87, v87
	v_fmac_f32_e32 v203, v84, v84
	v_fmac_f32_e32 v214, v86, v86
	v_add_f32_e32 v203, v203, v214
	v_mul_f32_e32 v214, v77, v77
	v_fmac_f32_e32 v214, v76, v76
	v_add_f32_e32 v203, v203, v214
	v_mul_f32_e32 v214, v79, v79
	v_fmac_f32_e32 v214, v78, v78
	v_add_f32_e32 v203, v214, v203
	v_mul_f32_e32 v204, v81, v81
	v_mul_f32_e32 v214, v83, v83
	v_fmac_f32_e32 v204, v80, v80
	v_fmac_f32_e32 v214, v82, v82
	v_add_f32_e32 v204, v204, v214
	v_mul_f32_e32 v214, v73, v73
	v_fmac_f32_e32 v214, v72, v72
	v_add_f32_e32 v204, v204, v214
	v_mul_f32_e32 v214, v75, v75
	v_fmac_f32_e32 v214, v74, v74
	v_add_f32_e32 v204, v214, v204
	v_mul_f32_e32 v205, v69, v69
	v_mul_f32_e32 v214, v71, v71
	v_fmac_f32_e32 v205, v68, v68
	v_fmac_f32_e32 v214, v70, v70
	v_add_f32_e32 v205, v205, v214
	v_mul_f32_e32 v214, v65, v65
	v_fmac_f32_e32 v214, v64, v64
	v_add_f32_e32 v205, v205, v214
	v_mul_f32_e32 v214, v67, v67
	v_fmac_f32_e32 v214, v66, v66
	v_add_f32_e32 v205, v214, v205
	ds_swizzle_b32 v206, v198 offset:swizzle(SWAP,16)
	ds_swizzle_b32 v207, v199 offset:swizzle(SWAP,16)
	ds_swizzle_b32 v208, v200 offset:swizzle(SWAP,16)
	ds_swizzle_b32 v209, v201 offset:swizzle(SWAP,16)
	ds_swizzle_b32 v210, v202 offset:swizzle(SWAP,16)
	ds_swizzle_b32 v211, v203 offset:swizzle(SWAP,16)
	ds_swizzle_b32 v212, v204 offset:swizzle(SWAP,16)
	ds_swizzle_b32 v213, v205 offset:swizzle(SWAP,16)
	s_waitcnt lgkmcnt(7)
	v_add_f32_e32 v198, v198, v206
	s_waitcnt lgkmcnt(6)
	v_add_f32_e32 v199, v199, v207
	s_waitcnt lgkmcnt(5)
	v_add_f32_e32 v200, v200, v208
	s_waitcnt lgkmcnt(4)
	v_add_f32_e32 v201, v201, v209
	s_waitcnt lgkmcnt(3)
	v_add_f32_e32 v202, v202, v210
	s_waitcnt lgkmcnt(2)
	v_add_f32_e32 v203, v203, v211
	s_waitcnt lgkmcnt(1)
	v_add_f32_e32 v204, v204, v212
	s_waitcnt lgkmcnt(0)
	v_add_f32_e32 v205, v205, v213
	v_mov_b32_e32 v206, v198
	v_mov_b32_e32 v207, v199
	v_mov_b32_e32 v208, v200
	v_mov_b32_e32 v209, v201
	v_mov_b32_e32 v210, v202
	v_mov_b32_e32 v211, v203
	v_mov_b32_e32 v212, v204
	v_mov_b32_e32 v213, v205
	s_nop 1
	v_permlane32_swap_b32_e32 v198, v206
	v_permlane32_swap_b32_e32 v199, v207
	v_permlane32_swap_b32_e32 v200, v208
	v_permlane32_swap_b32_e32 v201, v209
	v_permlane32_swap_b32_e32 v202, v210
	v_permlane32_swap_b32_e32 v203, v211
	v_permlane32_swap_b32_e32 v204, v212
	v_permlane32_swap_b32_e32 v205, v213
	s_and_saveexec_b64 s[52:53], s[8:9]
	v_add_f32_e32 v198, v198, v206
	v_add_f32_e32 v199, v199, v207
	v_add_f32_e32 v200, v200, v208
	v_add_f32_e32 v201, v201, v209
	v_add_f32_e32 v202, v202, v210
	v_add_f32_e32 v203, v203, v211
	v_add_f32_e32 v204, v204, v212
	v_add_f32_e32 v205, v205, v213
	ds_write_b32 v172, v198
	ds_write_b32 v172, v199 offset:16
	ds_write_b32 v174, v200
	ds_write_b32 v174, v201 offset:16
	ds_write_b32 v176, v202
	ds_write_b32 v176, v203 offset:16
	ds_write_b32 v178, v204
	ds_write_b32 v178, v205 offset:16
	s_or_b64 exec, exec, s[52:53]
	v_mul_f32_e32 v198, v61, v61
	v_mul_f32_e32 v214, v63, v63
	v_fmac_f32_e32 v198, v60, v60
	v_fmac_f32_e32 v214, v62, v62
	v_add_f32_e32 v198, v198, v214
	v_mul_f32_e32 v214, v57, v57
	v_fmac_f32_e32 v214, v56, v56
	v_add_f32_e32 v198, v198, v214
	v_mul_f32_e32 v214, v59, v59
	v_fmac_f32_e32 v214, v58, v58
;     __device__ __forceinline__ void operator()(PG8_ACC, const Unit& u, int wr, int wc, int fr, int fq) const {
;     ...
;                         const f32x4 a = acc[ai][bj][m][0], b = acc[ai][bj][m][1];
;                         float s = (a[0] * a[0] + a[1] * a[1]) + (a[2] * a[2] + a[3] * a[3]) + (b[0] * b[0] + b[1] * b[1]) + (b[2] * b[2] + b[3] * b[3]);
;                         s += shx<16>(s); s = sum_halves(s);
;                         if (fq == 0) X[((ai * 128 + wr * 64 + m * 16 + fr) * 2 + bj) * 4 + wc] = s;
;                     }
;             asm volatile("s_waitcnt lgkmcnt(0)" ::: "memory"); __builtin_amdgcn_s_barrier(); asm volatile("" ::: "memory");
	v_add_f32_e32 v198, v214, v198
	v_mul_f32_e32 v199, v53, v53
	v_mul_f32_e32 v214, v55, v55
	v_fmac_f32_e32 v199, v52, v52
	v_fmac_f32_e32 v214, v54, v54
	v_add_f32_e32 v199, v199, v214
	v_mul_f32_e32 v214, v45, v45
	v_fmac_f32_e32 v214, v44, v44
	v_add_f32_e32 v199, v199, v214
	v_mul_f32_e32 v214, v47, v47
	v_fmac_f32_e32 v214, v46, v46
	v_add_f32_e32 v199, v214, v199
	v_mul_f32_e32 v200, v49, v49
	v_mul_f32_e32 v214, v51, v51
	v_fmac_f32_e32 v200, v48, v48
	v_fmac_f32_e32 v214, v50, v50
	v_add_f32_e32 v200, v200, v214
	v_mul_f32_e32 v214, v41, v41
	v_fmac_f32_e32 v214, v40, v40
	v_add_f32_e32 v200, v200, v214
	v_mul_f32_e32 v214, v43, v43
	v_fmac_f32_e32 v214, v42, v42
	v_add_f32_e32 v200, v214, v200
	v_mul_f32_e32 v201, v37, v37
	v_mul_f32_e32 v214, v39, v39
	v_fmac_f32_e32 v201, v36, v36
	v_fmac_f32_e32 v214, v38, v38
	v_add_f32_e32 v201, v201, v214
	v_mul_f32_e32 v214, v29, v29
	v_fmac_f32_e32 v214, v28, v28
	v_add_f32_e32 v201, v201, v214
	v_mul_f32_e32 v214, v31, v31
	v_fmac_f32_e32 v214, v30, v30
	v_add_f32_e32 v201, v214, v201
	v_mul_f32_e32 v202, v33, v33
	v_mul_f32_e32 v214, v35, v35
	v_fmac_f32_e32 v202, v32, v32
	v_fmac_f32_e32 v214, v34, v34
	v_add_f32_e32 v202, v202, v214
	v_mul_f32_e32 v214, v25, v25
	v_fmac_f32_e32 v214, v24, v24
	v_add_f32_e32 v202, v202, v214
	v_mul_f32_e32 v214, v27, v27
	v_fmac_f32_e32 v214, v26, v26
	v_add_f32_e32 v202, v214, v202
	v_mul_f32_e32 v203, v21, v21
	v_mul_f32_e32 v214, v23, v23
	v_fmac_f32_e32 v203, v20, v20
	v_fmac_f32_e32 v214, v22, v22
	v_add_f32_e32 v203, v203, v214
	v_mul_f32_e32 v214, v13, v13
	v_fmac_f32_e32 v214, v12, v12
	v_add_f32_e32 v203, v203, v214
	v_mul_f32_e32 v214, v15, v15
	v_fmac_f32_e32 v214, v14, v14
	v_add_f32_e32 v203, v214, v203
	v_mul_f32_e32 v204, v17, v17
	v_mul_f32_e32 v214, v19, v19
	v_fmac_f32_e32 v204, v16, v16
	v_fmac_f32_e32 v214, v18, v18
	v_add_f32_e32 v204, v204, v214
	v_mul_f32_e32 v214, v9, v9
	v_fmac_f32_e32 v214, v8, v8
	v_add_f32_e32 v204, v204, v214
	v_mul_f32_e32 v214, v11, v11
	v_fmac_f32_e32 v214, v10, v10
	v_add_f32_e32 v204, v214, v204
	v_mul_f32_e32 v205, v5, v5
	v_mul_f32_e32 v214, v7, v7
	v_fmac_f32_e32 v205, v4, v4
	v_fmac_f32_e32 v214, v6, v6
	v_add_f32_e32 v205, v205, v214
	v_mul_f32_e32 v214, v1, v1
	v_fmac_f32_e32 v214, v0, v0
	v_add_f32_e32 v205, v205, v214
	v_mul_f32_e32 v214, v3, v3
	v_fmac_f32_e32 v214, v2, v2
	v_add_f32_e32 v205, v214, v205
	ds_swizzle_b32 v206, v198 offset:swizzle(SWAP,16)
	ds_swizzle_b32 v207, v199 offset:swizzle(SWAP,16)
	ds_swizzle_b32 v208, v200 offset:swizzle(SWAP,16)
	ds_swizzle_b32 v209, v201 offset:swizzle(SWAP,16)
	ds_swizzle_b32 v210, v202 offset:swizzle(SWAP,16)
	ds_swizzle_b32 v211, v203 offset:swizzle(SWAP,16)
	ds_swizzle_b32 v212, v204 offset:swizzle(SWAP,16)
	ds_swizzle_b32 v213, v205 offset:swizzle(SWAP,16)
	s_waitcnt lgkmcnt(7)
	v_add_f32_e32 v198, v198, v206
	s_waitcnt lgkmcnt(6)
	v_add_f32_e32 v199, v199, v207
	s_waitcnt lgkmcnt(5)
	v_add_f32_e32 v200, v200, v208
	s_waitcnt lgkmcnt(4)
	v_add_f32_e32 v201, v201, v209
	s_waitcnt lgkmcnt(3)
	v_add_f32_e32 v202, v202, v210
	s_waitcnt lgkmcnt(2)
	v_add_f32_e32 v203, v203, v211
	s_waitcnt lgkmcnt(1)
	v_add_f32_e32 v204, v204, v212
	s_waitcnt lgkmcnt(0)
	v_add_f32_e32 v205, v205, v213
	v_mov_b32_e32 v206, v198
	v_mov_b32_e32 v207, v199
	v_mov_b32_e32 v208, v200
	v_mov_b32_e32 v209, v201
	v_mov_b32_e32 v210, v202
	v_mov_b32_e32 v211, v203
	v_mov_b32_e32 v212, v204
	v_mov_b32_e32 v213, v205
	s_nop 1
	v_permlane32_swap_b32_e32 v198, v206
	v_permlane32_swap_b32_e32 v199, v207
	v_permlane32_swap_b32_e32 v200, v208
	v_permlane32_swap_b32_e32 v201, v209
	v_permlane32_swap_b32_e32 v202, v210
	v_permlane32_swap_b32_e32 v203, v211
	v_permlane32_swap_b32_e32 v204, v212
	v_permlane32_swap_b32_e32 v205, v213
	s_and_saveexec_b64 s[52:53], s[8:9]
	v_add_f32_e32 v198, v198, v206
	v_add_f32_e32 v199, v199, v207
	v_add_f32_e32 v200, v200, v208
	v_add_f32_e32 v201, v201, v209
	v_add_f32_e32 v202, v202, v210
	v_add_f32_e32 v203, v203, v211
	v_add_f32_e32 v204, v204, v212
	v_add_f32_e32 v205, v205, v213
	ds_write_b32 v180, v198
	ds_write_b32 v180, v199 offset:16
	ds_write_b32 v182, v200
	ds_write_b32 v182, v201 offset:16
	ds_write_b32 v184, v202
	ds_write_b32 v184, v203 offset:16
	ds_write_b32 v186, v204
	ds_write_b32 v186, v205 offset:16
	s_or_b64 exec, exec, s[52:53]
	s_waitcnt lgkmcnt(0)
	s_barrier
; #define PG8_LAS __attribute__((address_space(3)))
;     __device__ __forceinline__ void operator()(PG8_ACC, const Unit& u, int wr, int wc, int fr, int fq) const {
;     ...
;             const int hd = (kind == 1) ? 64 : 128;
;             const float inv_hd = (kind == 1) ? (1.f / 64.f) : (1.f / 128.f);
; #pragma unroll
;             for (int ai = 0; ai < 2; ++ai)
; #pragma unroll
;                 for (int m = 0; m < 4; ++m)
; #pragma unroll
;                     for (int bj = 0; bj < 2; ++bj) {
;                         const f32x4 xs = *(const PG8_LAS f32x4*)(X + ((ai * 128 + wr * 64 + m * 16 + fr) * 2 + bj) * 4);
;                         float tot;
;                         if (kind == 1) tot = (wc < 2) ? (xs[0] + xs[1]) : (xs[2] + xs[3]);
;                         else tot = (xs[0] + xs[1]) + (xs[2] + xs[3]);
;                         rs[ai][m][bj] = __builtin_amdgcn_rsqf(tot * inv_hd + 1e-6f) * sc;
;                     }
;             const int gc = ((wc * 32 + 8 * fq) & (hd - 1));
;             gv[0] = *(const PG8_LAS f32x4*)(GT + gp + gc); gv[1] = *(const PG8_LAS f32x4*)(GT + gp + gc + 4);
	ds_read_b128 v[128:131], v171
	ds_read_b128 v[132:135], v171 offset:16
	v_cndmask_b32_e64 v151, v191, v192, s[50:51]
	s_and_b64 s[52:53], s[50:51], exec
	s_cselect_b32 s27, 56, 0x78
	s_waitcnt lgkmcnt(0)
	v_mov_b32_e32 v152, v129
	v_mov_b32_e32 v153, v130
	v_mov_b32_e32 v129, v131
	v_pk_add_f32 v[128:129], v[152:153], v[128:129]
	s_lshl_b32 s26, s26, 2
	v_cndmask_b32_e64 v130, v129, v128, s[4:5]
	v_add_f32_e32 v128, v128, v129
	v_cndmask_b32_e64 v128, v128, v130, s[50:51]
	v_fmaak_f32 v128, v151, v128, 0x358637bd
	v_rsq_f32_e32 v152, v128
	v_mov_b32_e32 v128, v133
	v_mov_b32_e32 v129, v134
	v_mov_b32_e32 v133, v135
	v_pk_add_f32 v[128:129], v[128:129], v[132:133]
	ds_read_b128 v[132:135], v173 offset:16
	v_cndmask_b32_e64 v130, v129, v128, s[4:5]
	v_add_f32_e32 v128, v128, v129
	v_cndmask_b32_e64 v128, v128, v130, s[50:51]
	v_fmaak_f32 v128, v151, v128, 0x358637bd
	v_rsq_f32_e32 v153, v128
	ds_read_b128 v[128:131], v173
	s_add_i32 s26, s26, 0
	v_pk_mul_f32 v[152:153], v[150:151], v[152:153] op_sel_hi:[0,1]
	s_waitcnt lgkmcnt(0)
	v_mov_b32_e32 v154, v129
	v_mov_b32_e32 v155, v130
	v_mov_b32_e32 v129, v131
	v_pk_add_f32 v[128:129], v[154:155], v[128:129]
	s_nop 0
	v_cndmask_b32_e64 v130, v129, v128, s[4:5]
	v_add_f32_e32 v128, v128, v129
	v_cndmask_b32_e64 v128, v128, v130, s[50:51]
	v_fmaak_f32 v128, v151, v128, 0x358637bd
	v_rsq_f32_e32 v154, v128
	v_mov_b32_e32 v128, v133
	v_mov_b32_e32 v129, v134
	v_mov_b32_e32 v133, v135
	v_pk_add_f32 v[128:129], v[128:129], v[132:133]
	s_nop 0
	v_cndmask_b32_e64 v132, v129, v128, s[4:5]
	v_add_f32_e32 v133, v128, v129
	ds_read_b128 v[128:131], v175
	v_cndmask_b32_e64 v132, v133, v132, s[50:51]
	v_fmaak_f32 v132, v151, v132, 0x358637bd
	v_rsq_f32_e32 v155, v132
	ds_read_b128 v[132:135], v175 offset:16
	s_waitcnt lgkmcnt(0)
	v_mov_b32_e32 v156, v129
	v_mov_b32_e32 v157, v130
	v_mov_b32_e32 v129, v131
	v_pk_add_f32 v[128:129], v[156:157], v[128:129]
	v_pk_mul_f32 v[166:167], v[150:151], v[154:155] op_sel_hi:[0,1]
	v_cndmask_b32_e64 v130, v129, v128, s[4:5]
	v_add_f32_e32 v128, v128, v129
	v_cndmask_b32_e64 v128, v128, v130, s[50:51]
	v_fmaak_f32 v128, v151, v128, 0x358637bd
	v_rsq_f32_e32 v156, v128
	v_mov_b32_e32 v128, v133
	v_mov_b32_e32 v129, v134
	v_mov_b32_e32 v133, v135
	v_pk_add_f32 v[128:129], v[128:129], v[132:133]
	s_nop 0
	v_cndmask_b32_e64 v132, v129, v128, s[4:5]
	v_add_f32_e32 v133, v128, v129
	ds_read_b128 v[128:131], v177
	v_cndmask_b32_e64 v132, v133, v132, s[50:51]
	v_fmaak_f32 v132, v151, v132, 0x358637bd
	v_rsq_f32_e32 v157, v132
	ds_read_b128 v[132:135], v177 offset:16
	s_waitcnt lgkmcnt(0)
	v_mov_b32_e32 v158, v129
	v_mov_b32_e32 v159, v130
	v_mov_b32_e32 v129, v131
	v_pk_add_f32 v[128:129], v[158:159], v[128:129]
	v_pk_mul_f32 v[162:163], v[150:151], v[156:157] op_sel_hi:[0,1]
	v_cndmask_b32_e64 v130, v129, v128, s[4:5]
	v_add_f32_e32 v128, v128, v129
	v_cndmask_b32_e64 v128, v128, v130, s[50:51]
	v_fmaak_f32 v128, v151, v128, 0x358637bd
	v_rsq_f32_e32 v158, v128
	v_mov_b32_e32 v128, v133
	v_mov_b32_e32 v129, v134
	v_mov_b32_e32 v133, v135
	v_pk_add_f32 v[128:129], v[128:129], v[132:133]
	ds_read_b128 v[132:135], v179 offset:16
	v_cndmask_b32_e64 v130, v129, v128, s[4:5]
	v_add_f32_e32 v128, v128, v129
	v_cndmask_b32_e64 v128, v128, v130, s[50:51]
	v_fmaak_f32 v128, v151, v128, 0x358637bd
	v_rsq_f32_e32 v159, v128
	ds_read_b128 v[128:131], v179
	v_pk_mul_f32 v[158:159], v[150:151], v[158:159] op_sel_hi:[0,1]
	s_waitcnt lgkmcnt(0)
	v_mov_b32_e32 v154, v129
	v_mov_b32_e32 v155, v130
	v_mov_b32_e32 v129, v131
	v_pk_add_f32 v[128:129], v[154:155], v[128:129]
	s_nop 0
	v_cndmask_b32_e64 v130, v129, v128, s[4:5]
	v_add_f32_e32 v128, v128, v129
	v_cndmask_b32_e64 v128, v128, v130, s[50:51]
	v_fmaak_f32 v128, v151, v128, 0x358637bd
	v_rsq_f32_e32 v154, v128
	v_mov_b32_e32 v128, v133
	v_mov_b32_e32 v129, v134
	v_mov_b32_e32 v133, v135
	v_pk_add_f32 v[128:129], v[128:129], v[132:133]
	s_nop 0
	v_cndmask_b32_e64 v132, v129, v128, s[4:5]
	v_add_f32_e32 v133, v128, v129
	ds_read_b128 v[128:131], v181
	v_cndmask_b32_e64 v132, v133, v132, s[50:51]
	v_fmaak_f32 v132, v151, v132, 0x358637bd
	v_rsq_f32_e32 v155, v132
	ds_read_b128 v[132:135], v181 offset:16
	s_waitcnt lgkmcnt(0)
	v_mov_b32_e32 v156, v129
	v_mov_b32_e32 v157, v130
	v_mov_b32_e32 v129, v131
	v_pk_add_f32 v[128:129], v[156:157], v[128:129]
	v_pk_mul_f32 v[164:165], v[150:151], v[154:155] op_sel_hi:[0,1]
	v_cndmask_b32_e64 v130, v129, v128, s[4:5]
	v_add_f32_e32 v128, v128, v129
	v_cndmask_b32_e64 v128, v128, v130, s[50:51]
	v_fmaak_f32 v128, v151, v128, 0x358637bd
	v_rsq_f32_e32 v156, v128
	v_mov_b32_e32 v128, v133
	v_mov_b32_e32 v129, v134
	v_mov_b32_e32 v133, v135
	v_pk_add_f32 v[128:129], v[128:129], v[132:133]
	s_nop 0
	v_cndmask_b32_e64 v132, v129, v128, s[4:5]
	v_add_f32_e32 v133, v128, v129
	ds_read_b128 v[128:131], v183
	v_cndmask_b32_e64 v132, v133, v132, s[50:51]
	v_fmaak_f32 v132, v151, v132, 0x358637bd
	v_rsq_f32_e32 v157, v132
	ds_read_b128 v[132:135], v183 offset:16
	s_waitcnt lgkmcnt(0)
	v_mov_b32_e32 v160, v129
	v_mov_b32_e32 v161, v130
	v_mov_b32_e32 v129, v131
	v_pk_add_f32 v[128:129], v[160:161], v[128:129]
	s_nop 0
	v_cndmask_b32_e64 v130, v129, v128, s[4:5]
	v_add_f32_e32 v128, v128, v129
	v_cndmask_b32_e64 v128, v128, v130, s[50:51]
	v_fmaak_f32 v128, v151, v128, 0x358637bd
	v_rsq_f32_e32 v194, v128
	v_mov_b32_e32 v128, v133
	v_mov_b32_e32 v129, v134
	v_mov_b32_e32 v133, v135
	v_pk_add_f32 v[128:129], v[128:129], v[132:133]
	s_nop 0
	v_cndmask_b32_e64 v132, v129, v128, s[4:5]
	v_add_f32_e32 v133, v128, v129
	ds_read_b128 v[128:131], v185
	v_cndmask_b32_e64 v132, v133, v132, s[50:51]
	v_fmaak_f32 v132, v151, v132, 0x358637bd
	v_rsq_f32_e32 v195, v132
	ds_read_b128 v[132:135], v185 offset:16
	s_waitcnt lgkmcnt(0)
	v_mov_b32_e32 v160, v129
	v_mov_b32_e32 v161, v130
	v_mov_b32_e32 v129, v131
	v_pk_add_f32 v[128:129], v[160:161], v[128:129]
	v_pk_mul_f32 v[160:161], v[150:151], v[156:157] op_sel_hi:[0,1]
	v_cndmask_b32_e64 v130, v129, v128, s[4:5]
	v_add_f32_e32 v128, v128, v129
	v_cndmask_b32_e64 v128, v128, v130, s[50:51]
	v_fmaak_f32 v128, v151, v128, 0x358637bd
	v_rsq_f32_e32 v196, v128
	v_mov_b32_e32 v128, v133
	v_mov_b32_e32 v129, v134
	v_mov_b32_e32 v133, v135
	v_pk_add_f32 v[128:129], v[128:129], v[132:133]
	v_pk_mul_f32 v[156:157], v[150:151], v[194:195] op_sel_hi:[0,1]
	v_cndmask_b32_e64 v130, v129, v128, s[4:5]
	v_add_f32_e32 v128, v128, v129
	v_cndmask_b32_e64 v128, v128, v130, s[50:51]
	v_fmaak_f32 v128, v151, v128, 0x358637bd
	v_rsq_f32_e32 v197, v128
	v_and_b32_e32 v128, s27, v170
	v_lshl_add_u32 v128, v128, 2, s26
	v_add_u32_e32 v128, 0x22000, v128
	ds_read_b128 v[132:135], v128
	ds_read_b128 v[128:131], v128 offset:16
	v_pk_mul_f32 v[154:155], v[150:151], v[196:197] op_sel_hi:[0,1]
